# FFN-up / projection epilogues end with s_waitcnt vmcnt(0): the tile's stores retire before the next tile's main loop instead of riding through its counted vmcnt waits
# speedup vs baseline: 1.0088x; 1.0088x over previous
.LBB0_237:
	v_bfe_u32 v246, v197, 4, 1
	v_mul_u32_u24_e32 v246, 0x15ff8, v246
	v_mov_b32_e32 v247, 0
	v_lshl_add_u32 v140, s41, 8, v145
	v_ashrrev_i32_e32 v141, 31, v140
	v_lshlrev_b64 v[164:165], 6, v[140:141]
	v_lshl_add_u64 v[164:165], s[66:67], 0, v[164:165]
	v_and_b32_e32 v166, 48, v197
	v_mov_b32_e32 v167, 0
	v_lshl_add_u64 v[164:165], v[164:165], 0, v[166:167]
	s_mov_b64 s[20:21], 0x2000
	v_lshl_add_u64 v[166:167], v[164:165], 0, s[20:21]
	v_lshl_or_b32 v142, s40, 7, v162
	v_ashrrev_i32_e32 v143, 31, v142
	v_lshlrev_b32_e32 v212, 5, v145
	v_add_u32_e32 v212, 0x20000, v212
	ds_read_b128 v[204:207], v212
	ds_read_b128 v[208:211], v212 offset:16
	s_waitcnt lgkmcnt(0)
	v_mov_b32_e32 v144, v204
	v_pk_mul_f32 v[126:127], v[126:127], v[144:145] op_sel_hi:[1,0]
	v_pk_mul_f32 v[122:123], v[122:123], v[144:145] op_sel_hi:[1,0]
	v_mul_f32_e32 v141, 0xbfb8aa3b, v126
	v_exp_f32_e32 v141, v141
	v_pk_mul_f32 v[124:125], v[124:125], v[144:145] op_sel_hi:[1,0]
	v_pk_mul_f32 v[118:119], v[118:119], v[144:145] op_sel_hi:[1,0]
	v_pk_mul_f32 v[114:115], v[114:115], v[144:145] op_sel_hi:[1,0]
	v_add_f32_e32 v141, 1.0, v141
	v_rcp_f32_e32 v164, v141
	v_mul_f32_e32 v141, 0xbfb8aa3b, v127
	v_exp_f32_e32 v141, v141
	v_pk_mul_f32 v[116:117], v[116:117], v[144:145] op_sel_hi:[1,0]
	v_add_f32_e32 v141, 1.0, v141
	v_rcp_f32_e32 v165, v141
	s_nop 0
	v_pk_mul_f32 v[126:127], v[126:127], v[164:165]
	s_nop 0
	v_pk_mul_f32 v[122:123], v[122:123], v[126:127]
	v_pk_mul_f32 v[126:127], v[128:129], v[144:145] op_sel_hi:[1,0]
	s_nop 0
	v_mul_f32_e32 v128, 0xbfb8aa3b, v126
	v_mul_f32_e32 v129, 0xbfb8aa3b, v127
	v_exp_f32_e32 v128, v128
	v_exp_f32_e32 v129, v129
	v_add_f32_e32 v128, 1.0, v128
	v_add_f32_e32 v129, 1.0, v129
	v_rcp_f32_e32 v128, v128
	v_rcp_f32_e32 v129, v129
	s_nop 0
	v_pk_mul_f32 v[126:127], v[126:127], v[128:129]
	s_nop 0
	v_pk_mul_f32 v[124:125], v[124:125], v[126:127]
	v_cvt_pk_bf16_f32 v126, v122, v123
	v_mov_b64_e32 v[122:123], s[8:9]
	v_cvt_pk_bf16_f32 v127, v124, v125
	v_mad_i64_i32 v[128:129], s[20:21], v140, s1, v[122:123]
	v_lshlrev_b64 v[124:125], 1, v[142:143]
	v_lshl_add_u64 v[128:129], v[128:129], 0, v[124:125]
	v_lshl_add_u64 v[244:245], v[128:129], 0, v[246:247]
	v_mov_b32_e32 v236, v126
	v_mov_b32_e32 v237, v127
	v_mul_f32_e32 v126, 0xbfb8aa3b, v118
	v_mul_f32_e32 v127, 0xbfb8aa3b, v119
	v_exp_f32_e32 v126, v126
	v_exp_f32_e32 v127, v127
	v_add_f32_e32 v126, 1.0, v126
	v_add_f32_e32 v127, 1.0, v127
	v_rcp_f32_e32 v126, v126
	v_rcp_f32_e32 v127, v127
	s_nop 0
	v_pk_mul_f32 v[118:119], v[118:119], v[126:127]
	s_nop 0
	v_pk_mul_f32 v[114:115], v[114:115], v[118:119]
	v_pk_mul_f32 v[118:119], v[120:121], v[144:145] op_sel_hi:[1,0]
	v_or_b32_e32 v126, 16, v140
	v_mul_f32_e32 v120, 0xbfb8aa3b, v118
	v_mul_f32_e32 v121, 0xbfb8aa3b, v119
	v_exp_f32_e32 v120, v120
	v_exp_f32_e32 v121, v121
	v_cvt_pk_bf16_f32 v114, v114, v115
	v_ashrrev_i32_e32 v127, 31, v126
	v_add_f32_e32 v120, 1.0, v120
	v_add_f32_e32 v121, 1.0, v121
	v_rcp_f32_e32 v120, v120
	v_rcp_f32_e32 v121, v121
	s_nop 0
	v_pk_mul_f32 v[118:119], v[118:119], v[120:121]
	s_nop 0
	v_pk_mul_f32 v[116:117], v[116:117], v[118:119]
	s_nop 0
	v_cvt_pk_bf16_f32 v115, v116, v117
	v_mov_b32_e32 v240, v114
	v_mov_b32_e32 v241, v115
	v_mov_b32_e32 v114, v205
	v_pk_mul_f32 v[110:111], v[110:111], v[114:115] op_sel_hi:[1,0]
	s_nop 0
	v_mul_f32_e32 v115, 0xbfb8aa3b, v110
	v_exp_f32_e32 v115, v115
	s_nop 0
	v_add_f32_e32 v115, 1.0, v115
	v_rcp_f32_e32 v116, v115
	v_mul_f32_e32 v115, 0xbfb8aa3b, v111
	v_exp_f32_e32 v115, v115
	s_nop 0
	v_add_f32_e32 v115, 1.0, v115
	v_rcp_f32_e32 v117, v115
	v_pk_mul_f32 v[106:107], v[106:107], v[114:115] op_sel_hi:[1,0]
	v_pk_mul_f32 v[108:109], v[108:109], v[114:115] op_sel_hi:[1,0]
	v_pk_mul_f32 v[102:103], v[102:103], v[114:115] op_sel_hi:[1,0]
	v_pk_mul_f32 v[110:111], v[110:111], v[116:117]
	v_pk_mul_f32 v[98:99], v[98:99], v[114:115] op_sel_hi:[1,0]
	v_pk_mul_f32 v[106:107], v[106:107], v[110:111]
	v_pk_mul_f32 v[110:111], v[112:113], v[114:115] op_sel_hi:[1,0]
	v_cvt_pk_bf16_f32 v106, v106, v107
	v_mul_f32_e32 v112, 0xbfb8aa3b, v110
	v_mul_f32_e32 v113, 0xbfb8aa3b, v111
	v_exp_f32_e32 v112, v112
	v_exp_f32_e32 v113, v113
	v_pk_mul_f32 v[100:101], v[100:101], v[114:115] op_sel_hi:[1,0]
	v_add_f32_e32 v112, 1.0, v112
	v_add_f32_e32 v113, 1.0, v113
	v_rcp_f32_e32 v112, v112
	v_rcp_f32_e32 v113, v113
	s_nop 0
	v_pk_mul_f32 v[110:111], v[110:111], v[112:113]
	s_nop 0
	v_pk_mul_f32 v[108:109], v[108:109], v[110:111]
	s_nop 0
	v_cvt_pk_bf16_f32 v107, v108, v109
	v_mad_i64_i32 v[108:109], s[20:21], v126, s1, v[122:123]
	v_lshl_add_u64 v[108:109], v[108:109], 0, v[124:125]
	v_mov_b32_e32 v238, v106
	v_mov_b32_e32 v239, v107
	s_nop 1
	v_permlane16_swap_b32_e32 v236, v238
	v_permlane16_swap_b32_e32 v237, v239
	global_store_dwordx4 v[244:245], v[236:239], off
	v_mul_f32_e32 v106, 0xbfb8aa3b, v102
	v_mul_f32_e32 v107, 0xbfb8aa3b, v103
	v_exp_f32_e32 v106, v106
	v_exp_f32_e32 v107, v107
	v_add_f32_e32 v106, 1.0, v106
	v_add_f32_e32 v107, 1.0, v107
	v_rcp_f32_e32 v106, v106
	v_rcp_f32_e32 v107, v107
	s_nop 0
	v_pk_mul_f32 v[102:103], v[102:103], v[106:107]
	s_nop 0
	v_pk_mul_f32 v[98:99], v[98:99], v[102:103]
	v_pk_mul_f32 v[102:103], v[104:105], v[114:115] op_sel_hi:[1,0]
	v_or_b32_e32 v106, 32, v140
	v_mul_f32_e32 v104, 0xbfb8aa3b, v102
	v_mul_f32_e32 v105, 0xbfb8aa3b, v103
	v_exp_f32_e32 v104, v104
	v_exp_f32_e32 v105, v105
	v_cvt_pk_bf16_f32 v98, v98, v99
	v_ashrrev_i32_e32 v107, 31, v106
	v_add_f32_e32 v104, 1.0, v104
	v_add_f32_e32 v105, 1.0, v105
	v_rcp_f32_e32 v104, v104
	v_rcp_f32_e32 v105, v105
	s_nop 0
	v_pk_mul_f32 v[102:103], v[102:103], v[104:105]
	s_nop 0
	v_pk_mul_f32 v[100:101], v[100:101], v[102:103]
	s_nop 0
	v_cvt_pk_bf16_f32 v99, v100, v101
	v_mov_b32_e32 v242, v98
	v_mov_b32_e32 v243, v99
	s_nop 1
	v_permlane16_swap_b32_e32 v240, v242
	v_permlane16_swap_b32_e32 v241, v243
	global_store_dwordx4 v[244:245], v[240:243], off offset:128
	v_mov_b32_e32 v98, v206
	v_pk_mul_f32 v[94:95], v[94:95], v[98:99] op_sel_hi:[1,0]
	s_nop 0
	v_mul_f32_e32 v99, 0xbfb8aa3b, v94
	v_exp_f32_e32 v99, v99
	s_nop 0
	v_add_f32_e32 v99, 1.0, v99
	v_rcp_f32_e32 v100, v99
	v_mul_f32_e32 v99, 0xbfb8aa3b, v95
	v_exp_f32_e32 v99, v99
	s_nop 0
	v_add_f32_e32 v99, 1.0, v99
	v_rcp_f32_e32 v101, v99
	v_pk_mul_f32 v[90:91], v[90:91], v[98:99] op_sel_hi:[1,0]
	v_pk_mul_f32 v[92:93], v[92:93], v[98:99] op_sel_hi:[1,0]
	v_pk_mul_f32 v[86:87], v[86:87], v[98:99] op_sel_hi:[1,0]
	v_pk_mul_f32 v[94:95], v[94:95], v[100:101]
	v_pk_mul_f32 v[82:83], v[82:83], v[98:99] op_sel_hi:[1,0]
	v_pk_mul_f32 v[90:91], v[90:91], v[94:95]
	v_pk_mul_f32 v[94:95], v[96:97], v[98:99] op_sel_hi:[1,0]
	v_cvt_pk_bf16_f32 v90, v90, v91
	v_mul_f32_e32 v96, 0xbfb8aa3b, v94
	v_mul_f32_e32 v97, 0xbfb8aa3b, v95
	v_exp_f32_e32 v96, v96
	v_exp_f32_e32 v97, v97
	v_pk_mul_f32 v[84:85], v[84:85], v[98:99] op_sel_hi:[1,0]
	v_add_f32_e32 v96, 1.0, v96
	v_add_f32_e32 v97, 1.0, v97
	v_rcp_f32_e32 v96, v96
	v_rcp_f32_e32 v97, v97
	s_nop 0
	v_pk_mul_f32 v[94:95], v[94:95], v[96:97]
	s_nop 0
	v_pk_mul_f32 v[92:93], v[92:93], v[94:95]
	s_nop 0
	v_cvt_pk_bf16_f32 v91, v92, v93
	v_mad_i64_i32 v[92:93], s[20:21], v106, s1, v[122:123]
	v_lshl_add_u64 v[92:93], v[92:93], 0, v[124:125]
	v_lshl_add_u64 v[244:245], v[92:93], 0, v[246:247]
	v_mov_b32_e32 v236, v90
	v_mov_b32_e32 v237, v91
	v_mul_f32_e32 v90, 0xbfb8aa3b, v86
	v_mul_f32_e32 v91, 0xbfb8aa3b, v87
	v_exp_f32_e32 v90, v90
	v_exp_f32_e32 v91, v91
	v_add_f32_e32 v90, 1.0, v90
	v_add_f32_e32 v91, 1.0, v91
	v_rcp_f32_e32 v90, v90
	v_rcp_f32_e32 v91, v91
	s_nop 0
	v_pk_mul_f32 v[86:87], v[86:87], v[90:91]
	s_nop 0
	v_pk_mul_f32 v[82:83], v[82:83], v[86:87]
	v_pk_mul_f32 v[86:87], v[88:89], v[98:99] op_sel_hi:[1,0]
	v_or_b32_e32 v90, 48, v140
	v_mul_f32_e32 v88, 0xbfb8aa3b, v86
	v_mul_f32_e32 v89, 0xbfb8aa3b, v87
	v_exp_f32_e32 v88, v88
	v_exp_f32_e32 v89, v89
	v_cvt_pk_bf16_f32 v82, v82, v83
	v_ashrrev_i32_e32 v91, 31, v90
	v_add_f32_e32 v88, 1.0, v88
	v_add_f32_e32 v89, 1.0, v89
	v_rcp_f32_e32 v88, v88
	v_rcp_f32_e32 v89, v89
	s_nop 0
	v_pk_mul_f32 v[86:87], v[86:87], v[88:89]
	s_nop 0
	v_pk_mul_f32 v[84:85], v[84:85], v[86:87]
	s_nop 0
	v_cvt_pk_bf16_f32 v83, v84, v85
	v_mov_b32_e32 v240, v82
	v_mov_b32_e32 v241, v83
	v_mov_b32_e32 v82, v207
	v_pk_mul_f32 v[78:79], v[78:79], v[82:83] op_sel_hi:[1,0]
	s_nop 0
	v_mul_f32_e32 v83, 0xbfb8aa3b, v78
	v_exp_f32_e32 v83, v83
	s_nop 0
	v_add_f32_e32 v83, 1.0, v83
	v_rcp_f32_e32 v84, v83
	v_mul_f32_e32 v83, 0xbfb8aa3b, v79
	v_exp_f32_e32 v83, v83
	s_nop 0
	v_add_f32_e32 v83, 1.0, v83
	v_rcp_f32_e32 v85, v83
	v_pk_mul_f32 v[74:75], v[74:75], v[82:83] op_sel_hi:[1,0]
	v_pk_mul_f32 v[76:77], v[76:77], v[82:83] op_sel_hi:[1,0]
	v_pk_mul_f32 v[70:71], v[70:71], v[82:83] op_sel_hi:[1,0]
	v_pk_mul_f32 v[78:79], v[78:79], v[84:85]
	v_pk_mul_f32 v[66:67], v[66:67], v[82:83] op_sel_hi:[1,0]
	v_pk_mul_f32 v[74:75], v[74:75], v[78:79]
	v_pk_mul_f32 v[78:79], v[80:81], v[82:83] op_sel_hi:[1,0]
	v_cvt_pk_bf16_f32 v74, v74, v75
	v_mul_f32_e32 v80, 0xbfb8aa3b, v78
	v_mul_f32_e32 v81, 0xbfb8aa3b, v79
	v_exp_f32_e32 v80, v80
	v_exp_f32_e32 v81, v81
	v_pk_mul_f32 v[68:69], v[68:69], v[82:83] op_sel_hi:[1,0]
	v_add_f32_e32 v80, 1.0, v80
	v_add_f32_e32 v81, 1.0, v81
	v_rcp_f32_e32 v80, v80
	v_rcp_f32_e32 v81, v81
	s_nop 0
	v_pk_mul_f32 v[78:79], v[78:79], v[80:81]
	s_nop 0
	v_pk_mul_f32 v[76:77], v[76:77], v[78:79]
	s_nop 0
	v_cvt_pk_bf16_f32 v75, v76, v77
	v_mad_i64_i32 v[76:77], s[20:21], v90, s1, v[122:123]
	v_lshl_add_u64 v[76:77], v[76:77], 0, v[124:125]
	v_mov_b32_e32 v238, v74
	v_mov_b32_e32 v239, v75
	s_nop 1
	v_permlane16_swap_b32_e32 v236, v238
	v_permlane16_swap_b32_e32 v237, v239
	global_store_dwordx4 v[244:245], v[236:239], off
	v_mul_f32_e32 v74, 0xbfb8aa3b, v70
	v_mul_f32_e32 v75, 0xbfb8aa3b, v71
	v_exp_f32_e32 v74, v74
	v_exp_f32_e32 v75, v75
	v_add_f32_e32 v74, 1.0, v74
	v_add_f32_e32 v75, 1.0, v75
	v_rcp_f32_e32 v74, v74
	v_rcp_f32_e32 v75, v75
	s_nop 0
	v_pk_mul_f32 v[70:71], v[70:71], v[74:75]
	s_nop 0
	v_pk_mul_f32 v[66:67], v[66:67], v[70:71]
	v_pk_mul_f32 v[70:71], v[72:73], v[82:83] op_sel_hi:[1,0]
	v_add_u32_e32 v74, 0x80, v140
	v_mul_f32_e32 v72, 0xbfb8aa3b, v70
	v_mul_f32_e32 v73, 0xbfb8aa3b, v71
	v_exp_f32_e32 v72, v72
	v_exp_f32_e32 v73, v73
	v_cvt_pk_bf16_f32 v66, v66, v67
	v_ashrrev_i32_e32 v75, 31, v74
	v_add_f32_e32 v72, 1.0, v72
	v_add_f32_e32 v73, 1.0, v73
	v_rcp_f32_e32 v72, v72
	v_rcp_f32_e32 v73, v73
	s_nop 0
	v_pk_mul_f32 v[70:71], v[70:71], v[72:73]
	s_nop 0
	v_pk_mul_f32 v[68:69], v[68:69], v[70:71]
	s_nop 0
	v_cvt_pk_bf16_f32 v67, v68, v69
	v_mov_b32_e32 v242, v66
	v_mov_b32_e32 v243, v67
	s_nop 1
	v_permlane16_swap_b32_e32 v240, v242
	v_permlane16_swap_b32_e32 v241, v243
	global_store_dwordx4 v[244:245], v[240:243], off offset:128
	v_mov_b32_e32 v66, v208
	v_pk_mul_f32 v[62:63], v[62:63], v[66:67] op_sel_hi:[1,0]
	s_nop 0
	v_mul_f32_e32 v67, 0xbfb8aa3b, v62
	v_exp_f32_e32 v67, v67
	s_nop 0
	v_add_f32_e32 v67, 1.0, v67
	v_rcp_f32_e32 v68, v67
	v_mul_f32_e32 v67, 0xbfb8aa3b, v63
	v_exp_f32_e32 v67, v67
	s_nop 0
	v_add_f32_e32 v67, 1.0, v67
	v_rcp_f32_e32 v69, v67
	v_pk_mul_f32 v[58:59], v[58:59], v[66:67] op_sel_hi:[1,0]
	v_pk_mul_f32 v[60:61], v[60:61], v[66:67] op_sel_hi:[1,0]
	v_pk_mul_f32 v[54:55], v[54:55], v[66:67] op_sel_hi:[1,0]
	v_pk_mul_f32 v[62:63], v[62:63], v[68:69]
	v_pk_mul_f32 v[50:51], v[50:51], v[66:67] op_sel_hi:[1,0]
	v_pk_mul_f32 v[58:59], v[58:59], v[62:63]
	v_pk_mul_f32 v[62:63], v[64:65], v[66:67] op_sel_hi:[1,0]
	v_cvt_pk_bf16_f32 v58, v58, v59
	v_mul_f32_e32 v64, 0xbfb8aa3b, v62
	v_mul_f32_e32 v65, 0xbfb8aa3b, v63
	v_exp_f32_e32 v64, v64
	v_exp_f32_e32 v65, v65
	v_pk_mul_f32 v[52:53], v[52:53], v[66:67] op_sel_hi:[1,0]
	v_add_f32_e32 v64, 1.0, v64
	v_add_f32_e32 v65, 1.0, v65
	v_rcp_f32_e32 v64, v64
	v_rcp_f32_e32 v65, v65
	s_nop 0
	v_pk_mul_f32 v[62:63], v[62:63], v[64:65]
	s_nop 0
	v_pk_mul_f32 v[60:61], v[60:61], v[62:63]
	s_nop 0
	v_cvt_pk_bf16_f32 v59, v60, v61
	v_mad_i64_i32 v[60:61], s[20:21], v74, s1, v[122:123]
	v_lshl_add_u64 v[60:61], v[60:61], 0, v[124:125]
	v_lshl_add_u64 v[244:245], v[60:61], 0, v[246:247]
	v_mov_b32_e32 v236, v58
	v_mov_b32_e32 v237, v59
	v_mul_f32_e32 v58, 0xbfb8aa3b, v54
	v_mul_f32_e32 v59, 0xbfb8aa3b, v55
	v_exp_f32_e32 v58, v58
	v_exp_f32_e32 v59, v59
	v_add_f32_e32 v58, 1.0, v58
	v_add_f32_e32 v59, 1.0, v59
	v_rcp_f32_e32 v58, v58
	v_rcp_f32_e32 v59, v59
	s_nop 0
	v_pk_mul_f32 v[54:55], v[54:55], v[58:59]
	s_nop 0
	v_pk_mul_f32 v[50:51], v[50:51], v[54:55]
	v_pk_mul_f32 v[54:55], v[56:57], v[66:67] op_sel_hi:[1,0]
	v_add_u32_e32 v58, 0x90, v140
	v_mul_f32_e32 v56, 0xbfb8aa3b, v54
	v_mul_f32_e32 v57, 0xbfb8aa3b, v55
	v_exp_f32_e32 v56, v56
	v_exp_f32_e32 v57, v57
	v_cvt_pk_bf16_f32 v50, v50, v51
	v_ashrrev_i32_e32 v59, 31, v58
	v_add_f32_e32 v56, 1.0, v56
	v_add_f32_e32 v57, 1.0, v57
	v_rcp_f32_e32 v56, v56
	v_rcp_f32_e32 v57, v57
	s_nop 0
	v_pk_mul_f32 v[54:55], v[54:55], v[56:57]
	s_nop 0
	v_pk_mul_f32 v[52:53], v[52:53], v[54:55]
	s_nop 0
	v_cvt_pk_bf16_f32 v51, v52, v53
	v_mov_b32_e32 v240, v50
	v_mov_b32_e32 v241, v51
	v_mov_b32_e32 v50, v209
	v_pk_mul_f32 v[46:47], v[46:47], v[50:51] op_sel_hi:[1,0]
	s_nop 0
	v_mul_f32_e32 v51, 0xbfb8aa3b, v46
	v_exp_f32_e32 v51, v51
	s_nop 0
	v_add_f32_e32 v51, 1.0, v51
	v_rcp_f32_e32 v52, v51
	v_mul_f32_e32 v51, 0xbfb8aa3b, v47
	v_exp_f32_e32 v51, v51
	s_nop 0
	v_add_f32_e32 v51, 1.0, v51
	v_rcp_f32_e32 v53, v51
	v_pk_mul_f32 v[42:43], v[42:43], v[50:51] op_sel_hi:[1,0]
	v_pk_mul_f32 v[44:45], v[44:45], v[50:51] op_sel_hi:[1,0]
	v_pk_mul_f32 v[38:39], v[38:39], v[50:51] op_sel_hi:[1,0]
	v_pk_mul_f32 v[46:47], v[46:47], v[52:53]
	v_pk_mul_f32 v[34:35], v[34:35], v[50:51] op_sel_hi:[1,0]
	v_pk_mul_f32 v[42:43], v[42:43], v[46:47]
	v_pk_mul_f32 v[46:47], v[48:49], v[50:51] op_sel_hi:[1,0]
	v_cvt_pk_bf16_f32 v42, v42, v43
	v_mul_f32_e32 v48, 0xbfb8aa3b, v46
	v_mul_f32_e32 v49, 0xbfb8aa3b, v47
	v_exp_f32_e32 v48, v48
	v_exp_f32_e32 v49, v49
	v_pk_mul_f32 v[36:37], v[36:37], v[50:51] op_sel_hi:[1,0]
	v_add_f32_e32 v48, 1.0, v48
	v_add_f32_e32 v49, 1.0, v49
	v_rcp_f32_e32 v48, v48
	v_rcp_f32_e32 v49, v49
	s_nop 0
	v_pk_mul_f32 v[46:47], v[46:47], v[48:49]
	s_nop 0
	v_pk_mul_f32 v[44:45], v[44:45], v[46:47]
	s_nop 0
	v_cvt_pk_bf16_f32 v43, v44, v45
	v_mad_i64_i32 v[44:45], s[20:21], v58, s1, v[122:123]
	v_lshl_add_u64 v[44:45], v[44:45], 0, v[124:125]
	v_mov_b32_e32 v238, v42
	v_mov_b32_e32 v239, v43
	s_nop 1
	v_permlane16_swap_b32_e32 v236, v238
	v_permlane16_swap_b32_e32 v237, v239
	global_store_dwordx4 v[244:245], v[236:239], off
	v_mul_f32_e32 v42, 0xbfb8aa3b, v38
	v_mul_f32_e32 v43, 0xbfb8aa3b, v39
	v_exp_f32_e32 v42, v42
	v_exp_f32_e32 v43, v43
	v_add_f32_e32 v42, 1.0, v42
	v_add_f32_e32 v43, 1.0, v43
	v_rcp_f32_e32 v42, v42
	v_rcp_f32_e32 v43, v43
	s_nop 0
	v_pk_mul_f32 v[38:39], v[38:39], v[42:43]
	s_nop 0
	v_pk_mul_f32 v[34:35], v[34:35], v[38:39]
	v_pk_mul_f32 v[38:39], v[40:41], v[50:51] op_sel_hi:[1,0]
	v_add_u32_e32 v42, 0xa0, v140
	v_mul_f32_e32 v40, 0xbfb8aa3b, v38
	v_mul_f32_e32 v41, 0xbfb8aa3b, v39
	v_exp_f32_e32 v40, v40
	v_exp_f32_e32 v41, v41
	v_cvt_pk_bf16_f32 v34, v34, v35
	v_ashrrev_i32_e32 v43, 31, v42
	v_add_f32_e32 v40, 1.0, v40
	v_add_f32_e32 v41, 1.0, v41
	v_rcp_f32_e32 v40, v40
	v_rcp_f32_e32 v41, v41
	s_nop 0
	v_pk_mul_f32 v[38:39], v[38:39], v[40:41]
	s_nop 0
	v_pk_mul_f32 v[36:37], v[36:37], v[38:39]
	s_nop 0
	v_cvt_pk_bf16_f32 v35, v36, v37
	v_mov_b32_e32 v242, v34
	v_mov_b32_e32 v243, v35
	s_nop 1
	v_permlane16_swap_b32_e32 v240, v242
	v_permlane16_swap_b32_e32 v241, v243
	global_store_dwordx4 v[244:245], v[240:243], off offset:128
	v_mov_b32_e32 v34, v210
	v_pk_mul_f32 v[30:31], v[30:31], v[34:35] op_sel_hi:[1,0]
	s_nop 0
	v_mul_f32_e32 v35, 0xbfb8aa3b, v30
	v_exp_f32_e32 v35, v35
	s_nop 0
	v_add_f32_e32 v35, 1.0, v35
	v_rcp_f32_e32 v36, v35
	v_mul_f32_e32 v35, 0xbfb8aa3b, v31
	v_exp_f32_e32 v35, v35
	s_nop 0
	v_add_f32_e32 v35, 1.0, v35
	v_rcp_f32_e32 v37, v35
	v_pk_mul_f32 v[26:27], v[26:27], v[34:35] op_sel_hi:[1,0]
	v_pk_mul_f32 v[28:29], v[28:29], v[34:35] op_sel_hi:[1,0]
	v_pk_mul_f32 v[22:23], v[22:23], v[34:35] op_sel_hi:[1,0]
	v_pk_mul_f32 v[30:31], v[30:31], v[36:37]
	v_pk_mul_f32 v[18:19], v[18:19], v[34:35] op_sel_hi:[1,0]
	v_pk_mul_f32 v[26:27], v[26:27], v[30:31]
	v_pk_mul_f32 v[30:31], v[32:33], v[34:35] op_sel_hi:[1,0]
	v_cvt_pk_bf16_f32 v26, v26, v27
	v_mul_f32_e32 v32, 0xbfb8aa3b, v30
	v_mul_f32_e32 v33, 0xbfb8aa3b, v31
	v_exp_f32_e32 v32, v32
	v_exp_f32_e32 v33, v33
	v_pk_mul_f32 v[20:21], v[20:21], v[34:35] op_sel_hi:[1,0]
	v_add_f32_e32 v32, 1.0, v32
	v_add_f32_e32 v33, 1.0, v33
	v_rcp_f32_e32 v32, v32
	v_rcp_f32_e32 v33, v33
	s_nop 0
	v_pk_mul_f32 v[30:31], v[30:31], v[32:33]
	s_nop 0
	v_pk_mul_f32 v[28:29], v[28:29], v[30:31]
	s_nop 0
	v_cvt_pk_bf16_f32 v27, v28, v29
	v_mad_i64_i32 v[28:29], s[20:21], v42, s1, v[122:123]
	v_lshl_add_u64 v[28:29], v[28:29], 0, v[124:125]
	v_lshl_add_u64 v[244:245], v[28:29], 0, v[246:247]
	v_mov_b32_e32 v236, v26
	v_mov_b32_e32 v237, v27
	v_mul_f32_e32 v26, 0xbfb8aa3b, v22
	v_mul_f32_e32 v27, 0xbfb8aa3b, v23
	v_exp_f32_e32 v26, v26
	v_exp_f32_e32 v27, v27
	v_add_f32_e32 v26, 1.0, v26
	v_add_f32_e32 v27, 1.0, v27
	v_rcp_f32_e32 v26, v26
	v_rcp_f32_e32 v27, v27
	s_nop 0
	v_pk_mul_f32 v[22:23], v[22:23], v[26:27]
	s_nop 0
	v_pk_mul_f32 v[18:19], v[18:19], v[22:23]
	v_pk_mul_f32 v[22:23], v[24:25], v[34:35] op_sel_hi:[1,0]
	v_add_u32_e32 v26, 0xb0, v140
	v_mul_f32_e32 v24, 0xbfb8aa3b, v22
	v_mul_f32_e32 v25, 0xbfb8aa3b, v23
	v_exp_f32_e32 v24, v24
	v_exp_f32_e32 v25, v25
	v_cvt_pk_bf16_f32 v18, v18, v19
	v_ashrrev_i32_e32 v27, 31, v26
	v_add_f32_e32 v24, 1.0, v24
	v_add_f32_e32 v25, 1.0, v25
	v_rcp_f32_e32 v24, v24
	v_rcp_f32_e32 v25, v25
	s_nop 0
	v_pk_mul_f32 v[22:23], v[22:23], v[24:25]
	s_nop 0
	v_pk_mul_f32 v[20:21], v[20:21], v[22:23]
	s_nop 0
	v_cvt_pk_bf16_f32 v19, v20, v21
	v_mov_b32_e32 v240, v18
	v_mov_b32_e32 v241, v19
	v_mov_b32_e32 v18, v211
	v_pk_mul_f32 v[14:15], v[14:15], v[18:19] op_sel_hi:[1,0]
	s_andn2_b64 vcc, exec, s[4:5]
	v_mul_f32_e32 v19, 0xbfb8aa3b, v14
	v_exp_f32_e32 v19, v19
	s_nop 0
	v_add_f32_e32 v19, 1.0, v19
	v_rcp_f32_e32 v20, v19
	v_mul_f32_e32 v19, 0xbfb8aa3b, v15
	v_exp_f32_e32 v19, v19
	s_nop 0
	v_add_f32_e32 v19, 1.0, v19
	v_rcp_f32_e32 v21, v19
	v_pk_mul_f32 v[10:11], v[10:11], v[18:19] op_sel_hi:[1,0]
	v_pk_mul_f32 v[12:13], v[12:13], v[18:19] op_sel_hi:[1,0]
	v_pk_mul_f32 v[6:7], v[6:7], v[18:19] op_sel_hi:[1,0]
	v_pk_mul_f32 v[14:15], v[14:15], v[20:21]
	v_pk_mul_f32 v[2:3], v[2:3], v[18:19] op_sel_hi:[1,0]
	v_pk_mul_f32 v[10:11], v[10:11], v[14:15]
	v_pk_mul_f32 v[14:15], v[16:17], v[18:19] op_sel_hi:[1,0]
	v_cvt_pk_bf16_f32 v10, v10, v11
	v_mul_f32_e32 v16, 0xbfb8aa3b, v14
	v_mul_f32_e32 v17, 0xbfb8aa3b, v15
	v_exp_f32_e32 v16, v16
	v_exp_f32_e32 v17, v17
	v_pk_mul_f32 v[4:5], v[4:5], v[18:19] op_sel_hi:[1,0]
	v_add_f32_e32 v16, 1.0, v16
	v_add_f32_e32 v17, 1.0, v17
	v_rcp_f32_e32 v16, v16
	v_rcp_f32_e32 v17, v17
	s_nop 0
	v_pk_mul_f32 v[14:15], v[14:15], v[16:17]
	s_nop 0
	v_pk_mul_f32 v[12:13], v[12:13], v[14:15]
	s_nop 0
	v_cvt_pk_bf16_f32 v11, v12, v13
	v_mad_i64_i32 v[12:13], s[20:21], v26, s1, v[122:123]
	v_lshl_add_u64 v[12:13], v[12:13], 0, v[124:125]
	v_mov_b32_e32 v238, v10
	v_mov_b32_e32 v239, v11
	s_nop 1
	v_permlane16_swap_b32_e32 v236, v238
	v_permlane16_swap_b32_e32 v237, v239
	global_store_dwordx4 v[244:245], v[236:239], off
	v_mul_f32_e32 v10, 0xbfb8aa3b, v6
	v_mul_f32_e32 v11, 0xbfb8aa3b, v7
	v_exp_f32_e32 v10, v10
	v_exp_f32_e32 v11, v11
	s_mov_b64 s[20:21], -1
	v_add_f32_e32 v10, 1.0, v10
	v_add_f32_e32 v11, 1.0, v11
	v_rcp_f32_e32 v10, v10
	v_rcp_f32_e32 v11, v11
	s_nop 0
	v_pk_mul_f32 v[6:7], v[6:7], v[10:11]
	s_nop 0
	v_pk_mul_f32 v[2:3], v[2:3], v[6:7]
	v_pk_mul_f32 v[6:7], v[8:9], v[18:19] op_sel_hi:[1,0]
	v_cvt_pk_bf16_f32 v2, v2, v3
	v_mul_f32_e32 v8, 0xbfb8aa3b, v6
	v_mul_f32_e32 v9, 0xbfb8aa3b, v7
	v_exp_f32_e32 v8, v8
	v_exp_f32_e32 v9, v9
	v_add_f32_e32 v8, 1.0, v8
	v_add_f32_e32 v9, 1.0, v9
	v_rcp_f32_e32 v8, v8
	v_rcp_f32_e32 v9, v9
	s_nop 0
	v_pk_mul_f32 v[6:7], v[6:7], v[8:9]
	s_nop 0
	v_pk_mul_f32 v[4:5], v[4:5], v[6:7]
	s_nop 0
	v_cvt_pk_bf16_f32 v3, v4, v5
	v_mov_b32_e32 v242, v2
	v_mov_b32_e32 v243, v3
	s_nop 1
	v_permlane16_swap_b32_e32 v240, v242
	v_permlane16_swap_b32_e32 v241, v243
	global_store_dwordx4 v[244:245], v[240:243], off offset:128
	s_waitcnt vmcnt(0)
	s_cbranch_vccnz .LBB0_230
	s_andn2_b64 vcc, exec, s[6:7]
	s_cbranch_vccnz .LBB0_229
	s_barrier
	s_branch .LBB0_229

.LBB0_493:
	v_cvt_pk_bf16_f32 v2, v12, v14
	v_cvt_pk_bf16_f32 v3, v16, v19
	v_cvt_pk_bf16_f32 v4, v13, v15
	v_cvt_pk_bf16_f32 v5, v17, v18
	s_andn2_b64 vcc, exec, s[8:9]
	s_mov_b64 s[8:9], -1
	global_store_dwordx4 v[10:11], v[2:5], off offset:256
	s_waitcnt vmcnt(0)
	s_cbranch_vccnz .LBB0_390
	s_andn2_b64 vcc, exec, s[4:5]
	s_cbranch_vccnz .LBB0_389
	s_barrier
	s_branch .LBB0_389

.LBB0_1605:
	v_bfe_u32 v246, v197, 4, 1
	v_mul_u32_u24_e32 v246, 0x15ff8, v246
	v_mov_b32_e32 v247, 0
	v_lshl_add_u32 v140, s41, 8, v145
	v_ashrrev_i32_e32 v141, 31, v140
	v_lshlrev_b64 v[164:165], 6, v[140:141]
	v_lshl_add_u64 v[164:165], s[66:67], 0, v[164:165]
	v_and_b32_e32 v166, 48, v197
	v_mov_b32_e32 v167, 0
	v_lshl_add_u64 v[164:165], v[164:165], 0, v[166:167]
	s_mov_b64 s[20:21], 0x2000
	v_lshl_add_u64 v[166:167], v[164:165], 0, s[20:21]
	v_lshl_or_b32 v142, s40, 7, v162
	v_ashrrev_i32_e32 v143, 31, v142
	v_lshlrev_b32_e32 v212, 5, v145
	v_add_u32_e32 v212, 0x20000, v212
	ds_read_b128 v[204:207], v212
	ds_read_b128 v[208:211], v212 offset:16
	s_waitcnt lgkmcnt(0)
	v_mov_b32_e32 v144, v204
	v_pk_mul_f32 v[126:127], v[126:127], v[144:145] op_sel_hi:[1,0]
	v_pk_mul_f32 v[122:123], v[122:123], v[144:145] op_sel_hi:[1,0]
	v_mul_f32_e32 v141, 0xbfb8aa3b, v126
	v_exp_f32_e32 v141, v141
	v_pk_mul_f32 v[124:125], v[124:125], v[144:145] op_sel_hi:[1,0]
	v_pk_mul_f32 v[118:119], v[118:119], v[144:145] op_sel_hi:[1,0]
	v_pk_mul_f32 v[114:115], v[114:115], v[144:145] op_sel_hi:[1,0]
	v_add_f32_e32 v141, 1.0, v141
	v_rcp_f32_e32 v164, v141
	v_mul_f32_e32 v141, 0xbfb8aa3b, v127
	v_exp_f32_e32 v141, v141
	v_pk_mul_f32 v[116:117], v[116:117], v[144:145] op_sel_hi:[1,0]
	v_add_f32_e32 v141, 1.0, v141
	v_rcp_f32_e32 v165, v141
	s_nop 0
	v_pk_mul_f32 v[126:127], v[126:127], v[164:165]
	s_nop 0
	v_pk_mul_f32 v[122:123], v[122:123], v[126:127]
	v_pk_mul_f32 v[126:127], v[128:129], v[144:145] op_sel_hi:[1,0]
	s_nop 0
	v_mul_f32_e32 v128, 0xbfb8aa3b, v126
	v_mul_f32_e32 v129, 0xbfb8aa3b, v127
	v_exp_f32_e32 v128, v128
	v_exp_f32_e32 v129, v129
	v_add_f32_e32 v128, 1.0, v128
	v_add_f32_e32 v129, 1.0, v129
	v_rcp_f32_e32 v128, v128
	v_rcp_f32_e32 v129, v129
	s_nop 0
	v_pk_mul_f32 v[126:127], v[126:127], v[128:129]
	s_nop 0
	v_pk_mul_f32 v[124:125], v[124:125], v[126:127]
	v_cvt_pk_bf16_f32 v126, v122, v123
	v_mov_b64_e32 v[122:123], s[8:9]
	v_cvt_pk_bf16_f32 v127, v124, v125
	v_mad_i64_i32 v[128:129], s[20:21], v140, s1, v[122:123]
	v_lshlrev_b64 v[124:125], 1, v[142:143]
	v_lshl_add_u64 v[128:129], v[128:129], 0, v[124:125]
	v_lshl_add_u64 v[244:245], v[128:129], 0, v[246:247]
	v_mov_b32_e32 v236, v126
	v_mov_b32_e32 v237, v127
	v_mul_f32_e32 v126, 0xbfb8aa3b, v118
	v_mul_f32_e32 v127, 0xbfb8aa3b, v119
	v_exp_f32_e32 v126, v126
	v_exp_f32_e32 v127, v127
	v_add_f32_e32 v126, 1.0, v126
	v_add_f32_e32 v127, 1.0, v127
	v_rcp_f32_e32 v126, v126
	v_rcp_f32_e32 v127, v127
	s_nop 0
	v_pk_mul_f32 v[118:119], v[118:119], v[126:127]
	s_nop 0
	v_pk_mul_f32 v[114:115], v[114:115], v[118:119]
	v_pk_mul_f32 v[118:119], v[120:121], v[144:145] op_sel_hi:[1,0]
	v_or_b32_e32 v126, 16, v140
	v_mul_f32_e32 v120, 0xbfb8aa3b, v118
	v_mul_f32_e32 v121, 0xbfb8aa3b, v119
	v_exp_f32_e32 v120, v120
	v_exp_f32_e32 v121, v121
	v_cvt_pk_bf16_f32 v114, v114, v115
	v_ashrrev_i32_e32 v127, 31, v126
	v_add_f32_e32 v120, 1.0, v120
	v_add_f32_e32 v121, 1.0, v121
	v_rcp_f32_e32 v120, v120
	v_rcp_f32_e32 v121, v121
	s_nop 0
	v_pk_mul_f32 v[118:119], v[118:119], v[120:121]
	s_nop 0
	v_pk_mul_f32 v[116:117], v[116:117], v[118:119]
	s_nop 0
	v_cvt_pk_bf16_f32 v115, v116, v117
	v_mov_b32_e32 v240, v114
	v_mov_b32_e32 v241, v115
	v_mov_b32_e32 v114, v205
	v_pk_mul_f32 v[110:111], v[110:111], v[114:115] op_sel_hi:[1,0]
	s_nop 0
	v_mul_f32_e32 v115, 0xbfb8aa3b, v110
	v_exp_f32_e32 v115, v115
	s_nop 0
	v_add_f32_e32 v115, 1.0, v115
	v_rcp_f32_e32 v116, v115
	v_mul_f32_e32 v115, 0xbfb8aa3b, v111
	v_exp_f32_e32 v115, v115
	s_nop 0
	v_add_f32_e32 v115, 1.0, v115
	v_rcp_f32_e32 v117, v115
	v_pk_mul_f32 v[106:107], v[106:107], v[114:115] op_sel_hi:[1,0]
	v_pk_mul_f32 v[108:109], v[108:109], v[114:115] op_sel_hi:[1,0]
	v_pk_mul_f32 v[102:103], v[102:103], v[114:115] op_sel_hi:[1,0]
	v_pk_mul_f32 v[110:111], v[110:111], v[116:117]
	v_pk_mul_f32 v[98:99], v[98:99], v[114:115] op_sel_hi:[1,0]
	v_pk_mul_f32 v[106:107], v[106:107], v[110:111]
	v_pk_mul_f32 v[110:111], v[112:113], v[114:115] op_sel_hi:[1,0]
	v_cvt_pk_bf16_f32 v106, v106, v107
	v_mul_f32_e32 v112, 0xbfb8aa3b, v110
	v_mul_f32_e32 v113, 0xbfb8aa3b, v111
	v_exp_f32_e32 v112, v112
	v_exp_f32_e32 v113, v113
	v_pk_mul_f32 v[100:101], v[100:101], v[114:115] op_sel_hi:[1,0]
	v_add_f32_e32 v112, 1.0, v112
	v_add_f32_e32 v113, 1.0, v113
	v_rcp_f32_e32 v112, v112
	v_rcp_f32_e32 v113, v113
	s_nop 0
	v_pk_mul_f32 v[110:111], v[110:111], v[112:113]
	s_nop 0
	v_pk_mul_f32 v[108:109], v[108:109], v[110:111]
	s_nop 0
	v_cvt_pk_bf16_f32 v107, v108, v109
	v_mad_i64_i32 v[108:109], s[20:21], v126, s1, v[122:123]
	v_lshl_add_u64 v[108:109], v[108:109], 0, v[124:125]
	v_mov_b32_e32 v238, v106
	v_mov_b32_e32 v239, v107
	s_nop 1
	v_permlane16_swap_b32_e32 v236, v238
	v_permlane16_swap_b32_e32 v237, v239
	global_store_dwordx4 v[244:245], v[236:239], off
	v_mul_f32_e32 v106, 0xbfb8aa3b, v102
	v_mul_f32_e32 v107, 0xbfb8aa3b, v103
	v_exp_f32_e32 v106, v106
	v_exp_f32_e32 v107, v107
	v_add_f32_e32 v106, 1.0, v106
	v_add_f32_e32 v107, 1.0, v107
	v_rcp_f32_e32 v106, v106
	v_rcp_f32_e32 v107, v107
	s_nop 0
	v_pk_mul_f32 v[102:103], v[102:103], v[106:107]
	s_nop 0
	v_pk_mul_f32 v[98:99], v[98:99], v[102:103]
	v_pk_mul_f32 v[102:103], v[104:105], v[114:115] op_sel_hi:[1,0]
	v_or_b32_e32 v106, 32, v140
	v_mul_f32_e32 v104, 0xbfb8aa3b, v102
	v_mul_f32_e32 v105, 0xbfb8aa3b, v103
	v_exp_f32_e32 v104, v104
	v_exp_f32_e32 v105, v105
	v_cvt_pk_bf16_f32 v98, v98, v99
	v_ashrrev_i32_e32 v107, 31, v106
	v_add_f32_e32 v104, 1.0, v104
	v_add_f32_e32 v105, 1.0, v105
	v_rcp_f32_e32 v104, v104
	v_rcp_f32_e32 v105, v105
	s_nop 0
	v_pk_mul_f32 v[102:103], v[102:103], v[104:105]
	s_nop 0
	v_pk_mul_f32 v[100:101], v[100:101], v[102:103]
	s_nop 0
	v_cvt_pk_bf16_f32 v99, v100, v101
	v_mov_b32_e32 v242, v98
	v_mov_b32_e32 v243, v99
	s_nop 1
	v_permlane16_swap_b32_e32 v240, v242
	v_permlane16_swap_b32_e32 v241, v243
	global_store_dwordx4 v[244:245], v[240:243], off offset:128
	v_mov_b32_e32 v98, v206
	v_pk_mul_f32 v[94:95], v[94:95], v[98:99] op_sel_hi:[1,0]
	s_nop 0
	v_mul_f32_e32 v99, 0xbfb8aa3b, v94
	v_exp_f32_e32 v99, v99
	s_nop 0
	v_add_f32_e32 v99, 1.0, v99
	v_rcp_f32_e32 v100, v99
	v_mul_f32_e32 v99, 0xbfb8aa3b, v95
	v_exp_f32_e32 v99, v99
	s_nop 0
	v_add_f32_e32 v99, 1.0, v99
	v_rcp_f32_e32 v101, v99
	v_pk_mul_f32 v[90:91], v[90:91], v[98:99] op_sel_hi:[1,0]
	v_pk_mul_f32 v[92:93], v[92:93], v[98:99] op_sel_hi:[1,0]
	v_pk_mul_f32 v[86:87], v[86:87], v[98:99] op_sel_hi:[1,0]
	v_pk_mul_f32 v[94:95], v[94:95], v[100:101]
	v_pk_mul_f32 v[82:83], v[82:83], v[98:99] op_sel_hi:[1,0]
	v_pk_mul_f32 v[90:91], v[90:91], v[94:95]
	v_pk_mul_f32 v[94:95], v[96:97], v[98:99] op_sel_hi:[1,0]
	v_cvt_pk_bf16_f32 v90, v90, v91
	v_mul_f32_e32 v96, 0xbfb8aa3b, v94
	v_mul_f32_e32 v97, 0xbfb8aa3b, v95
	v_exp_f32_e32 v96, v96
	v_exp_f32_e32 v97, v97
	v_pk_mul_f32 v[84:85], v[84:85], v[98:99] op_sel_hi:[1,0]
	v_add_f32_e32 v96, 1.0, v96
	v_add_f32_e32 v97, 1.0, v97
	v_rcp_f32_e32 v96, v96
	v_rcp_f32_e32 v97, v97
	s_nop 0
	v_pk_mul_f32 v[94:95], v[94:95], v[96:97]
	s_nop 0
	v_pk_mul_f32 v[92:93], v[92:93], v[94:95]
	s_nop 0
	v_cvt_pk_bf16_f32 v91, v92, v93
	v_mad_i64_i32 v[92:93], s[20:21], v106, s1, v[122:123]
	v_lshl_add_u64 v[92:93], v[92:93], 0, v[124:125]
	v_lshl_add_u64 v[244:245], v[92:93], 0, v[246:247]
	v_mov_b32_e32 v236, v90
	v_mov_b32_e32 v237, v91
	v_mul_f32_e32 v90, 0xbfb8aa3b, v86
	v_mul_f32_e32 v91, 0xbfb8aa3b, v87
	v_exp_f32_e32 v90, v90
	v_exp_f32_e32 v91, v91
	v_add_f32_e32 v90, 1.0, v90
	v_add_f32_e32 v91, 1.0, v91
	v_rcp_f32_e32 v90, v90
	v_rcp_f32_e32 v91, v91
	s_nop 0
	v_pk_mul_f32 v[86:87], v[86:87], v[90:91]
	s_nop 0
	v_pk_mul_f32 v[82:83], v[82:83], v[86:87]
	v_pk_mul_f32 v[86:87], v[88:89], v[98:99] op_sel_hi:[1,0]
	v_or_b32_e32 v90, 48, v140
	v_mul_f32_e32 v88, 0xbfb8aa3b, v86
	v_mul_f32_e32 v89, 0xbfb8aa3b, v87
	v_exp_f32_e32 v88, v88
	v_exp_f32_e32 v89, v89
	v_cvt_pk_bf16_f32 v82, v82, v83
	v_ashrrev_i32_e32 v91, 31, v90
	v_add_f32_e32 v88, 1.0, v88
	v_add_f32_e32 v89, 1.0, v89
	v_rcp_f32_e32 v88, v88
	v_rcp_f32_e32 v89, v89
	s_nop 0
	v_pk_mul_f32 v[86:87], v[86:87], v[88:89]
	s_nop 0
	v_pk_mul_f32 v[84:85], v[84:85], v[86:87]
	s_nop 0
	v_cvt_pk_bf16_f32 v83, v84, v85
	v_mov_b32_e32 v240, v82
	v_mov_b32_e32 v241, v83
	v_mov_b32_e32 v82, v207
	v_pk_mul_f32 v[78:79], v[78:79], v[82:83] op_sel_hi:[1,0]
	s_nop 0
	v_mul_f32_e32 v83, 0xbfb8aa3b, v78
	v_exp_f32_e32 v83, v83
	s_nop 0
	v_add_f32_e32 v83, 1.0, v83
	v_rcp_f32_e32 v84, v83
	v_mul_f32_e32 v83, 0xbfb8aa3b, v79
	v_exp_f32_e32 v83, v83
	s_nop 0
	v_add_f32_e32 v83, 1.0, v83
	v_rcp_f32_e32 v85, v83
	v_pk_mul_f32 v[74:75], v[74:75], v[82:83] op_sel_hi:[1,0]
	v_pk_mul_f32 v[76:77], v[76:77], v[82:83] op_sel_hi:[1,0]
	v_pk_mul_f32 v[70:71], v[70:71], v[82:83] op_sel_hi:[1,0]
	v_pk_mul_f32 v[78:79], v[78:79], v[84:85]
	v_pk_mul_f32 v[66:67], v[66:67], v[82:83] op_sel_hi:[1,0]
	v_pk_mul_f32 v[74:75], v[74:75], v[78:79]
	v_pk_mul_f32 v[78:79], v[80:81], v[82:83] op_sel_hi:[1,0]
	v_cvt_pk_bf16_f32 v74, v74, v75
	v_mul_f32_e32 v80, 0xbfb8aa3b, v78
	v_mul_f32_e32 v81, 0xbfb8aa3b, v79
	v_exp_f32_e32 v80, v80
	v_exp_f32_e32 v81, v81
	v_pk_mul_f32 v[68:69], v[68:69], v[82:83] op_sel_hi:[1,0]
	v_add_f32_e32 v80, 1.0, v80
	v_add_f32_e32 v81, 1.0, v81
	v_rcp_f32_e32 v80, v80
	v_rcp_f32_e32 v81, v81
	s_nop 0
	v_pk_mul_f32 v[78:79], v[78:79], v[80:81]
	s_nop 0
	v_pk_mul_f32 v[76:77], v[76:77], v[78:79]
	s_nop 0
	v_cvt_pk_bf16_f32 v75, v76, v77
	v_mad_i64_i32 v[76:77], s[20:21], v90, s1, v[122:123]
	v_lshl_add_u64 v[76:77], v[76:77], 0, v[124:125]
	v_mov_b32_e32 v238, v74
	v_mov_b32_e32 v239, v75
	s_nop 1
	v_permlane16_swap_b32_e32 v236, v238
	v_permlane16_swap_b32_e32 v237, v239
	global_store_dwordx4 v[244:245], v[236:239], off
	v_mul_f32_e32 v74, 0xbfb8aa3b, v70
	v_mul_f32_e32 v75, 0xbfb8aa3b, v71
	v_exp_f32_e32 v74, v74
	v_exp_f32_e32 v75, v75
	v_add_f32_e32 v74, 1.0, v74
	v_add_f32_e32 v75, 1.0, v75
	v_rcp_f32_e32 v74, v74
	v_rcp_f32_e32 v75, v75
	s_nop 0
	v_pk_mul_f32 v[70:71], v[70:71], v[74:75]
	s_nop 0
	v_pk_mul_f32 v[66:67], v[66:67], v[70:71]
	v_pk_mul_f32 v[70:71], v[72:73], v[82:83] op_sel_hi:[1,0]
	v_add_u32_e32 v74, 0x80, v140
	v_mul_f32_e32 v72, 0xbfb8aa3b, v70
	v_mul_f32_e32 v73, 0xbfb8aa3b, v71
	v_exp_f32_e32 v72, v72
	v_exp_f32_e32 v73, v73
	v_cvt_pk_bf16_f32 v66, v66, v67
	v_ashrrev_i32_e32 v75, 31, v74
	v_add_f32_e32 v72, 1.0, v72
	v_add_f32_e32 v73, 1.0, v73
	v_rcp_f32_e32 v72, v72
	v_rcp_f32_e32 v73, v73
	s_nop 0
	v_pk_mul_f32 v[70:71], v[70:71], v[72:73]
	s_nop 0
	v_pk_mul_f32 v[68:69], v[68:69], v[70:71]
	s_nop 0
	v_cvt_pk_bf16_f32 v67, v68, v69
	v_mov_b32_e32 v242, v66
	v_mov_b32_e32 v243, v67
	s_nop 1
	v_permlane16_swap_b32_e32 v240, v242
	v_permlane16_swap_b32_e32 v241, v243
	global_store_dwordx4 v[244:245], v[240:243], off offset:128
	v_mov_b32_e32 v66, v208
	v_pk_mul_f32 v[62:63], v[62:63], v[66:67] op_sel_hi:[1,0]
	s_nop 0
	v_mul_f32_e32 v67, 0xbfb8aa3b, v62
	v_exp_f32_e32 v67, v67
	s_nop 0
	v_add_f32_e32 v67, 1.0, v67
	v_rcp_f32_e32 v68, v67
	v_mul_f32_e32 v67, 0xbfb8aa3b, v63
	v_exp_f32_e32 v67, v67
	s_nop 0
	v_add_f32_e32 v67, 1.0, v67
	v_rcp_f32_e32 v69, v67
	v_pk_mul_f32 v[58:59], v[58:59], v[66:67] op_sel_hi:[1,0]
	v_pk_mul_f32 v[60:61], v[60:61], v[66:67] op_sel_hi:[1,0]
	v_pk_mul_f32 v[54:55], v[54:55], v[66:67] op_sel_hi:[1,0]
	v_pk_mul_f32 v[62:63], v[62:63], v[68:69]
	v_pk_mul_f32 v[50:51], v[50:51], v[66:67] op_sel_hi:[1,0]
	v_pk_mul_f32 v[58:59], v[58:59], v[62:63]
	v_pk_mul_f32 v[62:63], v[64:65], v[66:67] op_sel_hi:[1,0]
	v_cvt_pk_bf16_f32 v58, v58, v59
	v_mul_f32_e32 v64, 0xbfb8aa3b, v62
	v_mul_f32_e32 v65, 0xbfb8aa3b, v63
	v_exp_f32_e32 v64, v64
	v_exp_f32_e32 v65, v65
	v_pk_mul_f32 v[52:53], v[52:53], v[66:67] op_sel_hi:[1,0]
	v_add_f32_e32 v64, 1.0, v64
	v_add_f32_e32 v65, 1.0, v65
	v_rcp_f32_e32 v64, v64
	v_rcp_f32_e32 v65, v65
	s_nop 0
	v_pk_mul_f32 v[62:63], v[62:63], v[64:65]
	s_nop 0
	v_pk_mul_f32 v[60:61], v[60:61], v[62:63]
	s_nop 0
	v_cvt_pk_bf16_f32 v59, v60, v61
	v_mad_i64_i32 v[60:61], s[20:21], v74, s1, v[122:123]
	v_lshl_add_u64 v[60:61], v[60:61], 0, v[124:125]
	v_lshl_add_u64 v[244:245], v[60:61], 0, v[246:247]
	v_mov_b32_e32 v236, v58
	v_mov_b32_e32 v237, v59
	v_mul_f32_e32 v58, 0xbfb8aa3b, v54
	v_mul_f32_e32 v59, 0xbfb8aa3b, v55
	v_exp_f32_e32 v58, v58
	v_exp_f32_e32 v59, v59
	v_add_f32_e32 v58, 1.0, v58
	v_add_f32_e32 v59, 1.0, v59
	v_rcp_f32_e32 v58, v58
	v_rcp_f32_e32 v59, v59
	s_nop 0
	v_pk_mul_f32 v[54:55], v[54:55], v[58:59]
	s_nop 0
	v_pk_mul_f32 v[50:51], v[50:51], v[54:55]
	v_pk_mul_f32 v[54:55], v[56:57], v[66:67] op_sel_hi:[1,0]
	v_add_u32_e32 v58, 0x90, v140
	v_mul_f32_e32 v56, 0xbfb8aa3b, v54
	v_mul_f32_e32 v57, 0xbfb8aa3b, v55
	v_exp_f32_e32 v56, v56
	v_exp_f32_e32 v57, v57
	v_cvt_pk_bf16_f32 v50, v50, v51
	v_ashrrev_i32_e32 v59, 31, v58
	v_add_f32_e32 v56, 1.0, v56
	v_add_f32_e32 v57, 1.0, v57
	v_rcp_f32_e32 v56, v56
	v_rcp_f32_e32 v57, v57
	s_nop 0
	v_pk_mul_f32 v[54:55], v[54:55], v[56:57]
	s_nop 0
	v_pk_mul_f32 v[52:53], v[52:53], v[54:55]
	s_nop 0
	v_cvt_pk_bf16_f32 v51, v52, v53
	v_mov_b32_e32 v240, v50
	v_mov_b32_e32 v241, v51
	v_mov_b32_e32 v50, v209
	v_pk_mul_f32 v[46:47], v[46:47], v[50:51] op_sel_hi:[1,0]
	s_nop 0
	v_mul_f32_e32 v51, 0xbfb8aa3b, v46
	v_exp_f32_e32 v51, v51
	s_nop 0
	v_add_f32_e32 v51, 1.0, v51
	v_rcp_f32_e32 v52, v51
	v_mul_f32_e32 v51, 0xbfb8aa3b, v47
	v_exp_f32_e32 v51, v51
	s_nop 0
	v_add_f32_e32 v51, 1.0, v51
	v_rcp_f32_e32 v53, v51
	v_pk_mul_f32 v[42:43], v[42:43], v[50:51] op_sel_hi:[1,0]
	v_pk_mul_f32 v[44:45], v[44:45], v[50:51] op_sel_hi:[1,0]
	v_pk_mul_f32 v[38:39], v[38:39], v[50:51] op_sel_hi:[1,0]
	v_pk_mul_f32 v[46:47], v[46:47], v[52:53]
	v_pk_mul_f32 v[34:35], v[34:35], v[50:51] op_sel_hi:[1,0]
	v_pk_mul_f32 v[42:43], v[42:43], v[46:47]
	v_pk_mul_f32 v[46:47], v[48:49], v[50:51] op_sel_hi:[1,0]
	v_cvt_pk_bf16_f32 v42, v42, v43
	v_mul_f32_e32 v48, 0xbfb8aa3b, v46
	v_mul_f32_e32 v49, 0xbfb8aa3b, v47
	v_exp_f32_e32 v48, v48
	v_exp_f32_e32 v49, v49
	v_pk_mul_f32 v[36:37], v[36:37], v[50:51] op_sel_hi:[1,0]
	v_add_f32_e32 v48, 1.0, v48
	v_add_f32_e32 v49, 1.0, v49
	v_rcp_f32_e32 v48, v48
	v_rcp_f32_e32 v49, v49
	s_nop 0
	v_pk_mul_f32 v[46:47], v[46:47], v[48:49]
	s_nop 0
	v_pk_mul_f32 v[44:45], v[44:45], v[46:47]
	s_nop 0
	v_cvt_pk_bf16_f32 v43, v44, v45
	v_mad_i64_i32 v[44:45], s[20:21], v58, s1, v[122:123]
	v_lshl_add_u64 v[44:45], v[44:45], 0, v[124:125]
	v_mov_b32_e32 v238, v42
	v_mov_b32_e32 v239, v43
	s_nop 1
	v_permlane16_swap_b32_e32 v236, v238
	v_permlane16_swap_b32_e32 v237, v239
	global_store_dwordx4 v[244:245], v[236:239], off
	v_mul_f32_e32 v42, 0xbfb8aa3b, v38
	v_mul_f32_e32 v43, 0xbfb8aa3b, v39
	v_exp_f32_e32 v42, v42
	v_exp_f32_e32 v43, v43
	v_add_f32_e32 v42, 1.0, v42
	v_add_f32_e32 v43, 1.0, v43
	v_rcp_f32_e32 v42, v42
	v_rcp_f32_e32 v43, v43
	s_nop 0
	v_pk_mul_f32 v[38:39], v[38:39], v[42:43]
	s_nop 0
	v_pk_mul_f32 v[34:35], v[34:35], v[38:39]
	v_pk_mul_f32 v[38:39], v[40:41], v[50:51] op_sel_hi:[1,0]
	v_add_u32_e32 v42, 0xa0, v140
	v_mul_f32_e32 v40, 0xbfb8aa3b, v38
	v_mul_f32_e32 v41, 0xbfb8aa3b, v39
	v_exp_f32_e32 v40, v40
	v_exp_f32_e32 v41, v41
	v_cvt_pk_bf16_f32 v34, v34, v35
	v_ashrrev_i32_e32 v43, 31, v42
	v_add_f32_e32 v40, 1.0, v40
	v_add_f32_e32 v41, 1.0, v41
	v_rcp_f32_e32 v40, v40
	v_rcp_f32_e32 v41, v41
	s_nop 0
	v_pk_mul_f32 v[38:39], v[38:39], v[40:41]
	s_nop 0
	v_pk_mul_f32 v[36:37], v[36:37], v[38:39]
	s_nop 0
	v_cvt_pk_bf16_f32 v35, v36, v37
	v_mov_b32_e32 v242, v34
	v_mov_b32_e32 v243, v35
	s_nop 1
	v_permlane16_swap_b32_e32 v240, v242
	v_permlane16_swap_b32_e32 v241, v243
	global_store_dwordx4 v[244:245], v[240:243], off offset:128
	v_mov_b32_e32 v34, v210
	v_pk_mul_f32 v[30:31], v[30:31], v[34:35] op_sel_hi:[1,0]
	s_nop 0
	v_mul_f32_e32 v35, 0xbfb8aa3b, v30
	v_exp_f32_e32 v35, v35
	s_nop 0
	v_add_f32_e32 v35, 1.0, v35
	v_rcp_f32_e32 v36, v35
	v_mul_f32_e32 v35, 0xbfb8aa3b, v31
	v_exp_f32_e32 v35, v35
	s_nop 0
	v_add_f32_e32 v35, 1.0, v35
	v_rcp_f32_e32 v37, v35
	v_pk_mul_f32 v[26:27], v[26:27], v[34:35] op_sel_hi:[1,0]
	v_pk_mul_f32 v[28:29], v[28:29], v[34:35] op_sel_hi:[1,0]
	v_pk_mul_f32 v[22:23], v[22:23], v[34:35] op_sel_hi:[1,0]
	v_pk_mul_f32 v[30:31], v[30:31], v[36:37]
	v_pk_mul_f32 v[18:19], v[18:19], v[34:35] op_sel_hi:[1,0]
	v_pk_mul_f32 v[26:27], v[26:27], v[30:31]
	v_pk_mul_f32 v[30:31], v[32:33], v[34:35] op_sel_hi:[1,0]
	v_cvt_pk_bf16_f32 v26, v26, v27
	v_mul_f32_e32 v32, 0xbfb8aa3b, v30
	v_mul_f32_e32 v33, 0xbfb8aa3b, v31
	v_exp_f32_e32 v32, v32
	v_exp_f32_e32 v33, v33
	v_pk_mul_f32 v[20:21], v[20:21], v[34:35] op_sel_hi:[1,0]
	v_add_f32_e32 v32, 1.0, v32
	v_add_f32_e32 v33, 1.0, v33
	v_rcp_f32_e32 v32, v32
	v_rcp_f32_e32 v33, v33
	s_nop 0
	v_pk_mul_f32 v[30:31], v[30:31], v[32:33]
	s_nop 0
	v_pk_mul_f32 v[28:29], v[28:29], v[30:31]
	s_nop 0
	v_cvt_pk_bf16_f32 v27, v28, v29
	v_mad_i64_i32 v[28:29], s[20:21], v42, s1, v[122:123]
	v_lshl_add_u64 v[28:29], v[28:29], 0, v[124:125]
	v_lshl_add_u64 v[244:245], v[28:29], 0, v[246:247]
	v_mov_b32_e32 v236, v26
	v_mov_b32_e32 v237, v27
	v_mul_f32_e32 v26, 0xbfb8aa3b, v22
	v_mul_f32_e32 v27, 0xbfb8aa3b, v23
	v_exp_f32_e32 v26, v26
	v_exp_f32_e32 v27, v27
	v_add_f32_e32 v26, 1.0, v26
	v_add_f32_e32 v27, 1.0, v27
	v_rcp_f32_e32 v26, v26
	v_rcp_f32_e32 v27, v27
	s_nop 0
	v_pk_mul_f32 v[22:23], v[22:23], v[26:27]
	s_nop 0
	v_pk_mul_f32 v[18:19], v[18:19], v[22:23]
	v_pk_mul_f32 v[22:23], v[24:25], v[34:35] op_sel_hi:[1,0]
	v_add_u32_e32 v26, 0xb0, v140
	v_mul_f32_e32 v24, 0xbfb8aa3b, v22
	v_mul_f32_e32 v25, 0xbfb8aa3b, v23
	v_exp_f32_e32 v24, v24
	v_exp_f32_e32 v25, v25
	v_cvt_pk_bf16_f32 v18, v18, v19
	v_ashrrev_i32_e32 v27, 31, v26
	v_add_f32_e32 v24, 1.0, v24
	v_add_f32_e32 v25, 1.0, v25
	v_rcp_f32_e32 v24, v24
	v_rcp_f32_e32 v25, v25
	s_nop 0
	v_pk_mul_f32 v[22:23], v[22:23], v[24:25]
	s_nop 0
	v_pk_mul_f32 v[20:21], v[20:21], v[22:23]
	s_nop 0
	v_cvt_pk_bf16_f32 v19, v20, v21
	v_mov_b32_e32 v240, v18
	v_mov_b32_e32 v241, v19
	v_mov_b32_e32 v18, v211
	v_pk_mul_f32 v[14:15], v[14:15], v[18:19] op_sel_hi:[1,0]
	s_andn2_b64 vcc, exec, s[6:7]
	v_mul_f32_e32 v19, 0xbfb8aa3b, v14
	v_exp_f32_e32 v19, v19
	s_nop 0
	v_add_f32_e32 v19, 1.0, v19
	v_rcp_f32_e32 v20, v19
	v_mul_f32_e32 v19, 0xbfb8aa3b, v15
	v_exp_f32_e32 v19, v19
	s_nop 0
	v_add_f32_e32 v19, 1.0, v19
	v_rcp_f32_e32 v21, v19
	v_pk_mul_f32 v[10:11], v[10:11], v[18:19] op_sel_hi:[1,0]
	v_pk_mul_f32 v[12:13], v[12:13], v[18:19] op_sel_hi:[1,0]
	v_pk_mul_f32 v[6:7], v[6:7], v[18:19] op_sel_hi:[1,0]
	v_pk_mul_f32 v[14:15], v[14:15], v[20:21]
	v_pk_mul_f32 v[2:3], v[2:3], v[18:19] op_sel_hi:[1,0]
	v_pk_mul_f32 v[10:11], v[10:11], v[14:15]
	v_pk_mul_f32 v[14:15], v[16:17], v[18:19] op_sel_hi:[1,0]
	v_cvt_pk_bf16_f32 v10, v10, v11
	v_mul_f32_e32 v16, 0xbfb8aa3b, v14
	v_mul_f32_e32 v17, 0xbfb8aa3b, v15
	v_exp_f32_e32 v16, v16
	v_exp_f32_e32 v17, v17
	v_pk_mul_f32 v[4:5], v[4:5], v[18:19] op_sel_hi:[1,0]
	v_add_f32_e32 v16, 1.0, v16
	v_add_f32_e32 v17, 1.0, v17
	v_rcp_f32_e32 v16, v16
	v_rcp_f32_e32 v17, v17
	s_nop 0
	v_pk_mul_f32 v[14:15], v[14:15], v[16:17]
	s_nop 0
	v_pk_mul_f32 v[12:13], v[12:13], v[14:15]
	s_nop 0
	v_cvt_pk_bf16_f32 v11, v12, v13
	v_mad_i64_i32 v[12:13], s[20:21], v26, s1, v[122:123]
	v_lshl_add_u64 v[12:13], v[12:13], 0, v[124:125]
	v_mov_b32_e32 v238, v10
	v_mov_b32_e32 v239, v11
	s_nop 1
	v_permlane16_swap_b32_e32 v236, v238
	v_permlane16_swap_b32_e32 v237, v239
	global_store_dwordx4 v[244:245], v[236:239], off
	v_mul_f32_e32 v10, 0xbfb8aa3b, v6
	v_mul_f32_e32 v11, 0xbfb8aa3b, v7
	v_exp_f32_e32 v10, v10
	v_exp_f32_e32 v11, v11
	s_mov_b64 s[20:21], -1
	v_add_f32_e32 v10, 1.0, v10
	v_add_f32_e32 v11, 1.0, v11
	v_rcp_f32_e32 v10, v10
	v_rcp_f32_e32 v11, v11
	s_nop 0
	v_pk_mul_f32 v[6:7], v[6:7], v[10:11]
	s_nop 0
	v_pk_mul_f32 v[2:3], v[2:3], v[6:7]
	v_pk_mul_f32 v[6:7], v[8:9], v[18:19] op_sel_hi:[1,0]
	v_cvt_pk_bf16_f32 v2, v2, v3
	v_mul_f32_e32 v8, 0xbfb8aa3b, v6
	v_mul_f32_e32 v9, 0xbfb8aa3b, v7
	v_exp_f32_e32 v8, v8
	v_exp_f32_e32 v9, v9
	v_add_f32_e32 v8, 1.0, v8
	v_add_f32_e32 v9, 1.0, v9
	v_rcp_f32_e32 v8, v8
	v_rcp_f32_e32 v9, v9
	s_nop 0
	v_pk_mul_f32 v[6:7], v[6:7], v[8:9]
	s_nop 0
	v_pk_mul_f32 v[4:5], v[4:5], v[6:7]
	s_nop 0
	v_cvt_pk_bf16_f32 v3, v4, v5
	v_mov_b32_e32 v242, v2
	v_mov_b32_e32 v243, v3
	s_nop 1
	v_permlane16_swap_b32_e32 v240, v242
	v_permlane16_swap_b32_e32 v241, v243
	global_store_dwordx4 v[244:245], v[240:243], off offset:128
	s_waitcnt vmcnt(0)
	s_cbranch_vccnz .LBB0_1598
	s_andn2_b64 vcc, exec, s[4:5]
	s_cbranch_vccnz .LBB0_1597
	s_barrier
	s_branch .LBB0_1597
